# v16 + mixer B second and third gate loads also issued at item start (third parked in a per-lane LDS slot)
# baseline (speedup 1.0000x reference)
.LBB0_1240:
	v_add_u32_e32 v0, 0x21300, v200
	ds_read_b32 v0, v0
	v_lshlrev_b64 v[72:73], 12, v[132:133]
	v_mov_b32_e32 v44, v35
	v_mov_b32_e32 v35, v47
	v_lshl_add_u64 v[46:47], s[24:25], 0, v[72:73]
	s_mov_b32 s73, s67
	v_ashrrev_i32_e32 v131, 31, v130
	v_lshl_add_u64 v[46:47], v[46:47], 0, s[72:73]
	s_mov_b64 s[8:9], 0x11c98800
	v_lshl_add_u64 v[46:47], v[130:131], 1, v[46:47]
	v_mov_b32_e32 v41, v51
	v_mov_b32_e32 v71, v52
	v_pk_mov_b32 v[50:51], v[52:53], v[50:51] op_sel:[1,0]
	v_lshl_add_u64 v[52:53], v[46:47], 0, s[8:9]
	s_mov_b32 s7, 0x11c98000
	ds_read2st64_b32 v[56:57], v200 offset0:168 offset1:176
	ds_read2st64_b32 v[58:59], v199 offset0:128 offset1:136
	ds_read2st64_b32 v[60:61], v200 offset0:184 offset1:192
	ds_read2st64_b32 v[62:63], v199 offset0:144 offset1:152
	ds_read2st64_b32 v[64:65], v200 offset0:200 offset1:208
	ds_read2st64_b32 v[66:67], v199 offset0:160 offset1:168
	ds_read2st64_b32 v[68:69], v200 offset0:216 offset1:224
	ds_read_b32 v70, v199 offset:45056
	s_waitcnt vmcnt(0) lgkmcnt(8)
	v_lshlrev_b32_e32 v0, 16, v0
	v_mul_f32_e32 v0, 0xbfb8aa3b, v0
	v_exp_f32_e32 v0, v0
	s_nop 0
	v_add_f32_e32 v0, 1.0, v0
	v_div_scale_f32 v55, s[10:11], v0, v0, 1.0
	v_rcp_f32_e32 v72, v55
	v_div_scale_f32 v73, vcc, 1.0, v0, 1.0
	v_fma_f32 v74, -v55, v72, 1.0
	v_fmac_f32_e32 v72, v74, v72
	v_mul_f32_e32 v74, v73, v72
	v_fma_f32 v75, -v55, v74, v73
	v_fmac_f32_e32 v74, v75, v72
	v_fma_f32 v55, -v55, v74, v73
	v_div_fmas_f32 v55, v55, v72, v74
	v_div_fixup_f32 v0, v55, v0, 1.0
	v_div_scale_f32 v55, s[8:9], v54, v54, v0
	v_rcp_f32_e32 v72, v55
	v_add_co_u32_e32 v46, vcc, s7, v46
	s_mov_b64 s[8:9], 0
	s_nop 0
	v_addc_co_u32_e32 v47, vcc, 0, v47, vcc
	v_fma_f32 v74, -v55, v72, 1.0
	v_div_scale_f32 v73, vcc, v0, v54, v0
	v_fmac_f32_e32 v72, v74, v72
	v_mul_f32_e32 v74, v73, v72
	v_fma_f32 v75, -v55, v74, v73
	v_fmac_f32_e32 v74, v75, v72
	v_fma_f32 v55, -v55, v74, v73
	v_div_fmas_f32 v55, v55, v72, v74
	v_div_fixup_f32 v0, v55, v54, v0
	s_waitcnt lgkmcnt(7)
	v_pk_fma_f32 v[2:3], v[2:3], v[0:1], v[56:57] op_sel_hi:[1,0,1]
	s_waitcnt lgkmcnt(5)
	v_pk_fma_f32 v[4:5], v[4:5], v[0:1], v[60:61] op_sel_hi:[1,0,1]
	s_waitcnt lgkmcnt(3)
	v_pk_fma_f32 v[6:7], v[6:7], v[0:1], v[64:65] op_sel_hi:[1,0,1]
	s_waitcnt lgkmcnt(1)
	v_pk_fma_f32 v[8:9], v[8:9], v[0:1], v[68:69] op_sel_hi:[1,0,1]
	v_pk_fma_f32 v[10:11], v[10:11], v[0:1], v[40:41] op_sel_hi:[1,0,1]
	v_pk_fma_f32 v[12:13], v[12:13], v[0:1], v[44:45] op_sel_hi:[1,0,1]
	v_pk_fma_f32 v[14:15], v[14:15], v[0:1], v[42:43] op_sel_hi:[1,0,1]
	v_pk_fma_f32 v[16:17], v[16:17], v[0:1], v[48:49] op_sel_hi:[1,0,1]
	v_pk_fma_f32 v[18:19], v[18:19], v[0:1], v[58:59] op_sel_hi:[1,0,1]
	v_pk_fma_f32 v[20:21], v[20:21], v[0:1], v[62:63] op_sel_hi:[1,0,1]
	v_pk_fma_f32 v[22:23], v[22:23], v[0:1], v[66:67] op_sel_hi:[1,0,1]
	s_waitcnt lgkmcnt(0)
	v_pk_fma_f32 v[24:25], v[24:25], v[0:1], v[70:71] op_sel_hi:[1,0,1]
	v_pk_fma_f32 v[26:27], v[26:27], v[0:1], v[50:51] op_sel_hi:[1,0,1]
	v_pk_fma_f32 v[28:29], v[28:29], v[0:1], v[34:35] op_sel_hi:[1,0,1]
	v_pk_fma_f32 v[30:31], v[30:31], v[0:1], v[38:39] op_sel_hi:[1,0,1]
	v_pk_fma_f32 v[32:33], v[32:33], v[0:1], v[36:37] op_sel_hi:[1,0,1]
	v_cvt_pk_bf16_f32 v2, v2, v3
	v_cvt_pk_bf16_f32 v3, v4, v5
	v_cvt_pk_bf16_f32 v4, v6, v7
	v_cvt_pk_bf16_f32 v5, v8, v9
	v_cvt_pk_bf16_f32 v6, v10, v11
	v_cvt_pk_bf16_f32 v7, v12, v13
	v_cvt_pk_bf16_f32 v8, v14, v15
	v_cvt_pk_bf16_f32 v9, v16, v17
	v_cvt_pk_bf16_f32 v10, v18, v19
	v_cvt_pk_bf16_f32 v11, v20, v21
	v_cvt_pk_bf16_f32 v12, v22, v23
	v_cvt_pk_bf16_f32 v13, v24, v25
	v_cvt_pk_bf16_f32 v14, v26, v27
	v_cvt_pk_bf16_f32 v15, v28, v29
	v_cvt_pk_bf16_f32 v16, v30, v31
	v_cvt_pk_bf16_f32 v17, v32, v33
	global_store_dwordx2 v[46:47], v[2:3], off offset:2048
	global_store_dwordx2 v[52:53], v[4:5], off offset:16
	global_store_dwordx2 v[52:53], v[6:7], off offset:32
	global_store_dwordx2 v[52:53], v[8:9], off offset:48
	global_store_dwordx2 v[52:53], v[10:11], off offset:64
	global_store_dwordx2 v[52:53], v[12:13], off offset:80
	global_store_dwordx2 v[52:53], v[14:15], off offset:96
	global_store_dwordx2 v[52:53], v[16:17], off offset:112

.LBB0_1252:
	s_or_b64 exec, exec, s[8:9]
	s_lshl_b32 s8, s7, 3
	s_or_b32 s8, s8, s56
	s_bfe_u32 s66, s8, 0x30001
	v_ashrrev_i32_e32 v86, 3, v87
	v_lshl_add_u32 v2, s66, 7, v86
	v_lshlrev_b32_e32 v0, 4, v84
	v_ashrrev_i32_e32 v3, 31, v2
	v_and_b32_e32 v131, 0x70, v0
	v_lshlrev_b64 v[10:11], 8, v[2:3]
	s_lshl_b32 s46, s6, 1
	v_or3_b32 v10, v131, s46, v10
	s_mov_b64 s[8:9], 0x4000
	v_lshl_add_u64 v[2:3], s[58:59], 0, v[10:11]
	v_lshl_add_u64 v[6:7], s[60:61], 0, v[10:11]
	v_lshl_add_u64 v[10:11], v[10:11], 0, s[8:9]
	v_lshl_add_u64 v[12:13], s[58:59], 0, v[10:11]
	v_lshl_add_u64 v[14:15], s[60:61], 0, v[10:11]
	global_load_dwordx4 v[2:5], v[2:3], off
	s_nop 0
	global_load_dwordx4 v[6:9], v[6:7], off
	s_nop 0
	global_load_dwordx4 v[10:13], v[12:13], off
	s_nop 0
	global_load_dwordx4 v[14:17], v[14:15], off
	s_lshl_b32 s7, s7, 4
	s_andn2_b32 s7, s7, 31
	s_sub_i32 s16, 0x7e0, s7
	v_and_b32_e32 v85, 31, v84
	v_or_b32_e32 v193, s16, v85
	v_ashrrev_i32_e32 v0, 5, v84
	v_lshl_add_u32 v132, s66, 11, v193
	v_mov_b64_e32 v[18:19], s[50:51]
	v_mad_i64_i32 v[82:83], s[8:9], v132, s84, v[18:19]
	s_lshl_b32 s72, s34, 1
	s_mov_b32 s73, s67
	v_lshlrev_b32_e32 v20, 3, v0
	v_lshl_add_u64 v[18:19], v[82:83], 0, s[72:73]
	v_ashrrev_i32_e32 v21, 31, v20
	v_lshl_add_u64 v[18:19], v[20:21], 1, v[18:19]
	global_load_dwordx4 v[98:101], v[18:19], off offset:2560
	global_load_dwordx4 v[102:105], v[18:19], off offset:2592
	global_load_dwordx4 v[106:109], v[18:19], off offset:2624
	global_load_dwordx4 v[110:113], v[18:19], off offset:2656
	v_lshrrev_b32_e32 v18, 2, v84
	v_lshlrev_b32_e32 v130, 2, v0
	v_mul_lo_u32 v194, v86, s86
	v_mul_lo_u32 v21, v86, 48
	v_and_or_b32 v22, v18, 3, v130
	v_add_u32_e32 v18, 0, v194
	v_lshlrev_b32_e32 v19, 1, v84
	v_add_u32_e32 v135, v18, v131
	v_add_u32_e32 v18, v18, v21
	s_movk_i32 s8, 0xffd0
	v_and_b32_e32 v20, 32, v19
	v_mad_u32_u24 v19, v85, s86, 0
	v_lshlrev_b32_e32 v195, 4, v0
	v_add_u32_e32 v134, v18, v131
	v_add_u32_e32 v42, v19, v195
	v_mad_u64_u32 v[18:19], s[8:9], v86, s8, v[134:135]
	v_add_u32_e32 v19, v18, v21
	s_waitcnt vmcnt(7)
	ds_write_b128 v135, v[2:5]
	s_waitcnt vmcnt(6)
	ds_write_b128 v134, v[6:9] offset:9216
	s_waitcnt vmcnt(5)
	ds_write_b128 v18, v[10:13] offset:21504
	s_waitcnt vmcnt(4)
	ds_write_b128 v19, v[14:17] offset:30720
	v_mov_b32_e32 v242, 0x1affc
	v_mov_b32_e32 v243, 0xf149f2ca
	ds_write_b32 v242, v243
	s_waitcnt lgkmcnt(0)
	s_barrier
	ds_read_b128 v[2:5], v42
	ds_read_b128 v[34:37], v42 offset:32
	ds_read_b128 v[6:9], v42 offset:4608
	ds_read_b128 v[38:41], v42 offset:4640
	ds_read_b128 v[44:47], v42 offset:64
	ds_read_b128 v[48:51], v42 offset:96
	ds_read_b128 v[52:55], v42 offset:4672
	ds_read_b128 v[56:59], v42 offset:4704
	v_lshlrev_b32_e32 v10, 3, v84
	v_and_b32_e32 v10, 24, v10
	v_mul_lo_u32 v11, v22, s85
	v_or3_b32 v196, v11, v20, v10
	s_waitcnt vmcnt(3) lgkmcnt(7)
	v_mfma_f32_32x32x16_bf16 v[18:33], v[2:5], v[98:101], 0
	s_waitcnt lgkmcnt(5)
	v_mfma_f32_32x32x16_bf16 v[2:17], v[6:9], v[98:101], 0
	s_waitcnt vmcnt(2)
	v_mfma_f32_32x32x16_bf16 v[18:33], v[34:37], v[102:105], v[18:33]
	s_waitcnt lgkmcnt(4)
	v_mfma_f32_32x32x16_bf16 v[2:17], v[38:41], v[102:105], v[2:17]
	s_waitcnt vmcnt(1) lgkmcnt(3)
	v_mfma_f32_32x32x16_bf16 v[18:33], v[44:47], v[106:109], v[18:33]
	v_add_u32_e32 v89, 0, v196
	ds_read_b64_tr_b16 v[34:35], v89 offset:9216
	ds_read_b64_tr_b16 v[36:37], v89 offset:10752
	ds_read_b64_tr_b16 v[40:41], v89 offset:10816
	ds_read_b64_tr_b16 v[38:39], v89 offset:9280
	v_subrev_u32_e32 v88, 31, v193
	v_lshlrev_b32_e32 v45, 6, v0
	v_sub_u32_e32 v46, v88, v45
	v_cmp_lt_i32_e32 vcc, -1, v46
	v_cmp_gt_i32_e64 s[8:9], 32, v0
	s_waitcnt lgkmcnt(5)
	v_mfma_f32_32x32x16_bf16 v[2:17], v[52:55], v[106:109], v[2:17]
	s_and_b64 s[10:11], s[8:9], vcc
	v_mov_b32_e32 v43, 0xf149f2ca
	v_mov_b32_e32 v44, 0xf149f2ca
	s_waitcnt vmcnt(0)
	s_add_i32 s100, s70, 0x1800
	s_mov_b32 s101, 0
	v_lshl_add_u64 v[244:245], v[82:83], 0, s[100:101]
	global_load_ushort v246, v[244:245], off
	global_load_ushort v247, v[244:245], off offset:2
	global_load_ushort v248, v[244:245], off offset:4
	v_mfma_f32_32x32x16_bf16 v[18:33], v[48:51], v[110:113], v[18:33]
	s_waitcnt lgkmcnt(4)
	v_mfma_f32_32x32x16_bf16 v[2:17], v[56:59], v[110:113], v[2:17]
	v_min_u32_e32 v210, 0x7f, v46
	v_lshl_add_u32 v210, v210, 2, s3
	v_cndmask_b32_e64 v210, v242, v210, s[10:11]
	ds_read_b32 v210, v210
	v_sub_u32_e32 v74, v193, v45
	v_add_u32_e32 v150, 0xfffffde1, v74
	v_cmp_lt_i32_e64 s[8:9], -1, v150
	v_cmp_gt_i32_e32 vcc, 24, v0
	s_and_b64 s[10:11], vcc, s[8:9]
	v_min_u32_e32 v211, 0x7f, v150
	v_lshl_add_u32 v211, v211, 2, s3
	v_cndmask_b32_e64 v211, v242, v211, s[10:11]
	ds_read_b32 v211, v211
	v_or_b32_e32 v151, 1, v130
	v_lshlrev_b32_e32 v152, 4, v151
	v_sub_u32_e32 v45, v88, v152
	v_cmp_lt_i32_e64 s[8:9], -1, v45
	v_cmp_gt_i32_e64 s[10:11], s82, v151
	s_and_b64 s[10:11], s[10:11], s[8:9]
	v_min_u32_e32 v212, 0x7f, v45
	v_lshl_add_u32 v212, v212, 2, s3
	v_cndmask_b32_e64 v212, v242, v212, s[10:11]
	ds_read_b32 v212, v212
	v_add_u32_e32 v153, 0xfffffdd1, v74
	v_cmp_lt_i32_e64 s[8:9], -1, v153
	s_and_b64 s[10:11], vcc, s[8:9]
	v_min_u32_e32 v213, 0x7f, v153
	v_lshl_add_u32 v213, v213, 2, s3
	v_cndmask_b32_e64 v213, v242, v213, s[10:11]
	ds_read_b32 v213, v213
	v_or_b32_e32 v154, 2, v130
	v_lshlrev_b32_e32 v155, 4, v154
	v_sub_u32_e32 v45, v88, v155
	v_cmp_lt_i32_e64 s[8:9], -1, v45
	v_cmp_gt_i32_e64 s[10:11], s82, v154
	s_and_b64 s[10:11], s[10:11], s[8:9]
	v_min_u32_e32 v214, 0x7f, v45
	v_lshl_add_u32 v214, v214, 2, s3
	v_cndmask_b32_e64 v214, v242, v214, s[10:11]
	ds_read_b32 v214, v214
	v_add_u32_e32 v156, 0xfffffdc1, v74
	v_cmp_lt_i32_e64 s[8:9], -1, v156
	s_and_b64 s[10:11], vcc, s[8:9]
	v_min_u32_e32 v215, 0x7f, v156
	v_lshl_add_u32 v215, v215, 2, s3
	v_cndmask_b32_e64 v215, v242, v215, s[10:11]
	ds_read_b32 v215, v215
	v_or_b32_e32 v157, 3, v130
	v_lshlrev_b32_e32 v158, 4, v157
	v_sub_u32_e32 v45, v88, v158
	v_cmp_lt_i32_e32 vcc, -1, v45
	v_cmp_gt_i32_e64 s[8:9], s82, v157
	s_and_b64 s[10:11], s[8:9], vcc
	v_min_u32_e32 v216, 0x7f, v45
	v_lshl_add_u32 v216, v216, 2, s3
	v_cndmask_b32_e64 v216, v242, v216, s[10:11]
	ds_read_b32 v216, v216
	v_add_u32_e32 v159, 0xfffffdb1, v74
	v_cmp_lt_i32_e32 vcc, -1, v159
	v_cmp_gt_i32_e64 s[8:9], 23, v0
	s_and_b64 s[10:11], s[8:9], vcc
	v_min_u32_e32 v217, 0x7f, v159
	v_lshl_add_u32 v217, v217, 2, s3
	v_cndmask_b32_e64 v217, v242, v217, s[10:11]
	ds_read_b32 v217, v217
	v_add_u32_e32 v45, 0xffffff61, v74
	v_cmp_lt_i32_e64 s[8:9], -1, v45
	v_cmp_gt_i32_e32 vcc, 30, v0
	s_and_b64 s[10:11], vcc, s[8:9]
	v_min_u32_e32 v218, 0x7f, v45
	v_lshl_add_u32 v218, v218, 2, s3
	v_cndmask_b32_e64 v218, v242, v218, s[10:11]
	ds_read_b32 v218, v218
	v_add_u32_e32 v160, 0xfffffd61, v74
	v_cmp_lt_i32_e64 s[10:11], -1, v160
	v_cmp_gt_i32_e64 s[8:9], 22, v0
	s_and_b64 s[12:13], s[8:9], s[10:11]
	v_min_u32_e32 v219, 0x7f, v160
	v_lshl_add_u32 v219, v219, 2, s3
	v_cndmask_b32_e64 v219, v242, v219, s[12:13]
	ds_read_b32 v219, v219
	v_add_u32_e32 v45, 0xffffff51, v74
	v_cmp_lt_i32_e64 s[10:11], -1, v45
	s_and_b64 s[12:13], vcc, s[10:11]
	v_min_u32_e32 v220, 0x7f, v45
	v_lshl_add_u32 v220, v220, 2, s3
	v_cndmask_b32_e64 v220, v242, v220, s[12:13]
	ds_read_b32 v220, v220
	v_add_u32_e32 v161, 0xfffffd51, v74
	v_cmp_lt_i32_e64 s[10:11], -1, v161
	s_and_b64 s[12:13], s[8:9], s[10:11]
	v_min_u32_e32 v221, 0x7f, v161
	v_lshl_add_u32 v221, v221, 2, s3
	v_cndmask_b32_e64 v221, v242, v221, s[12:13]
	ds_read_b32 v221, v221
	v_add_u32_e32 v45, 0xffffff41, v74
	v_cmp_lt_i32_e64 s[10:11], -1, v45
	s_and_b64 s[12:13], vcc, s[10:11]
	v_min_u32_e32 v222, 0x7f, v45
	v_lshl_add_u32 v222, v222, 2, s3
	v_cndmask_b32_e64 v222, v242, v222, s[12:13]
	ds_read_b32 v222, v222
	v_add_u32_e32 v162, 0xfffffd41, v74
	v_cmp_lt_i32_e32 vcc, -1, v162
	s_and_b64 s[10:11], s[8:9], vcc
	v_min_u32_e32 v223, 0x7f, v162
	v_lshl_add_u32 v223, v223, 2, s3
	v_cndmask_b32_e64 v223, v242, v223, s[10:11]
	ds_read_b32 v223, v223
	v_add_u32_e32 v45, 0xffffff31, v74
	v_cmp_lt_i32_e32 vcc, -1, v45
	v_cmp_gt_i32_e64 s[8:9], 29, v0
	s_and_b64 s[10:11], s[8:9], vcc
	v_min_u32_e32 v224, 0x7f, v45
	v_lshl_add_u32 v224, v224, 2, s3
	v_cndmask_b32_e64 v224, v242, v224, s[10:11]
	ds_read_b32 v224, v224
	v_add_u32_e32 v163, 0xfffffd31, v74
	v_cmp_lt_i32_e32 vcc, -1, v163
	v_cmp_gt_i32_e64 s[8:9], 21, v0
	s_and_b64 s[10:11], s[8:9], vcc
	v_min_u32_e32 v225, 0x7f, v163
	v_lshl_add_u32 v225, v225, 2, s3
	v_cndmask_b32_e64 v225, v242, v225, s[10:11]
	ds_read_b32 v225, v225
	v_add_u32_e32 v45, 0xfffffee1, v74
	v_cmp_lt_i32_e64 s[8:9], -1, v45
	v_cmp_gt_i32_e32 vcc, 28, v0
	s_and_b64 s[10:11], vcc, s[8:9]
	v_min_u32_e32 v226, 0x7f, v45
	v_lshl_add_u32 v226, v226, 2, s3
	v_cndmask_b32_e64 v226, v242, v226, s[10:11]
	ds_read_b32 v226, v226
	v_add_u32_e32 v164, 0xfffffce1, v74
	v_cmp_lt_i32_e64 s[10:11], -1, v164
	v_cmp_gt_i32_e64 s[8:9], 20, v0
	s_and_b64 s[12:13], s[8:9], s[10:11]
	v_min_u32_e32 v227, 0x7f, v164
	v_lshl_add_u32 v227, v227, 2, s3
	v_cndmask_b32_e64 v227, v242, v227, s[12:13]
	ds_read_b32 v227, v227
	v_add_u32_e32 v45, 0xfffffed1, v74
	v_cmp_lt_i32_e64 s[10:11], -1, v45
	s_and_b64 s[12:13], vcc, s[10:11]
	v_min_u32_e32 v228, 0x7f, v45
	v_lshl_add_u32 v228, v228, 2, s3
	v_cndmask_b32_e64 v228, v242, v228, s[12:13]
	ds_read_b32 v228, v228
	v_add_u32_e32 v165, 0xfffffcd1, v74
	v_cmp_lt_i32_e64 s[10:11], -1, v165
	s_and_b64 s[12:13], s[8:9], s[10:11]
	v_min_u32_e32 v229, 0x7f, v165
	v_lshl_add_u32 v229, v229, 2, s3
	v_cndmask_b32_e64 v229, v242, v229, s[12:13]
	ds_read_b32 v229, v229
	v_add_u32_e32 v45, 0xfffffec1, v74
	v_cmp_lt_i32_e64 s[10:11], -1, v45
	s_and_b64 s[12:13], vcc, s[10:11]
	v_min_u32_e32 v230, 0x7f, v45
	v_lshl_add_u32 v230, v230, 2, s3
	v_cndmask_b32_e64 v230, v242, v230, s[12:13]
	ds_read_b32 v230, v230
	v_add_u32_e32 v166, 0xfffffcc1, v74
	v_cmp_lt_i32_e32 vcc, -1, v166
	s_and_b64 s[10:11], s[8:9], vcc
	v_min_u32_e32 v231, 0x7f, v166
	v_lshl_add_u32 v231, v231, 2, s3
	v_cndmask_b32_e64 v231, v242, v231, s[10:11]
	ds_read_b32 v231, v231
	v_add_u32_e32 v45, 0xfffffeb1, v74
	v_cmp_lt_i32_e32 vcc, -1, v45
	v_cmp_gt_i32_e64 s[8:9], 27, v0
	s_and_b64 s[10:11], s[8:9], vcc
	v_min_u32_e32 v232, 0x7f, v45
	v_lshl_add_u32 v232, v232, 2, s3
	v_cndmask_b32_e64 v232, v242, v232, s[10:11]
	ds_read_b32 v232, v232
	v_add_u32_e32 v167, 0xfffffcb1, v74
	v_cmp_lt_i32_e32 vcc, -1, v167
	v_cmp_gt_i32_e64 s[8:9], 19, v0
	s_and_b64 s[10:11], s[8:9], vcc
	v_min_u32_e32 v233, 0x7f, v167
	v_lshl_add_u32 v233, v233, 2, s3
	v_cndmask_b32_e64 v233, v242, v233, s[10:11]
	ds_read_b32 v233, v233
	v_add_u32_e32 v45, 0xfffffe61, v74
	v_cmp_lt_i32_e64 s[8:9], -1, v45
	v_cmp_gt_i32_e32 vcc, 26, v0
	s_and_b64 s[10:11], vcc, s[8:9]
	v_min_u32_e32 v234, 0x7f, v45
	v_lshl_add_u32 v234, v234, 2, s3
	v_cndmask_b32_e64 v234, v242, v234, s[10:11]
	ds_read_b32 v234, v234
	v_add_u32_e32 v168, 0xfffffc61, v74
	v_cmp_lt_i32_e64 s[10:11], -1, v168
	v_cmp_gt_i32_e64 s[8:9], 18, v0
	s_and_b64 s[12:13], s[8:9], s[10:11]
	v_min_u32_e32 v235, 0x7f, v168
	v_lshl_add_u32 v235, v235, 2, s3
	v_cndmask_b32_e64 v235, v242, v235, s[12:13]
	ds_read_b32 v235, v235
	v_add_u32_e32 v45, 0xfffffe51, v74
	v_cmp_lt_i32_e64 s[10:11], -1, v45
	s_and_b64 s[12:13], vcc, s[10:11]
	v_min_u32_e32 v236, 0x7f, v45
	v_lshl_add_u32 v236, v236, 2, s3
	v_cndmask_b32_e64 v236, v242, v236, s[12:13]
	ds_read_b32 v236, v236
	v_add_u32_e32 v169, 0xfffffc51, v74
	v_cmp_lt_i32_e64 s[10:11], -1, v169
	s_and_b64 s[12:13], s[8:9], s[10:11]
	v_min_u32_e32 v237, 0x7f, v169
	v_lshl_add_u32 v237, v237, 2, s3
	v_cndmask_b32_e64 v237, v242, v237, s[12:13]
	ds_read_b32 v237, v237
	v_add_u32_e32 v45, 0xfffffe41, v74
	v_cmp_lt_i32_e64 s[10:11], -1, v45
	s_and_b64 s[12:13], vcc, s[10:11]
	v_min_u32_e32 v238, 0x7f, v45
	v_lshl_add_u32 v238, v238, 2, s3
	v_cndmask_b32_e64 v238, v242, v238, s[12:13]
	ds_read_b32 v238, v238
	v_add_u32_e32 v170, 0xfffffc41, v74
	v_cmp_lt_i32_e32 vcc, -1, v170
	s_and_b64 s[10:11], s[8:9], vcc
	v_min_u32_e32 v239, 0x7f, v170
	v_lshl_add_u32 v239, v239, 2, s3
	v_cndmask_b32_e64 v239, v242, v239, s[10:11]
	ds_read_b32 v239, v239
	v_add_u32_e32 v45, 0xfffffe31, v74
	v_cmp_lt_i32_e32 vcc, -1, v45
	v_cmp_gt_i32_e64 s[8:9], 25, v0
	s_and_b64 s[10:11], s[8:9], vcc
	v_min_u32_e32 v240, 0x7f, v45
	v_lshl_add_u32 v240, v240, 2, s3
	v_cndmask_b32_e64 v240, v242, v240, s[10:11]
	ds_read_b32 v240, v240
	v_add_u32_e32 v171, 0xfffffc31, v74
	v_cmp_lt_i32_e32 vcc, -1, v171
	v_cmp_gt_i32_e64 s[8:9], 17, v0
	s_and_b64 s[10:11], s[8:9], vcc
	v_min_u32_e32 v241, 0x7f, v171
	v_lshl_add_u32 v241, v241, 2, s3
	v_cndmask_b32_e64 v241, v242, v241, s[10:11]
	ds_read_b32 v241, v241
	s_waitcnt lgkmcnt(0)
	v_add_f32_e32 v44, v18, v210
	v_add_f32_e32 v43, v2, v211
	v_add_f32_e32 v18, v19, v212
	v_add_f32_e32 v2, v3, v213
	v_add_f32_e32 v19, v20, v214
	v_add_f32_e32 v3, v4, v215
	v_add_f32_e32 v20, v21, v216
	v_add_f32_e32 v4, v5, v217
	v_add_f32_e32 v21, v22, v218
	v_add_f32_e32 v5, v6, v219
	v_add_f32_e32 v22, v23, v220
	v_add_f32_e32 v6, v7, v221
	v_add_f32_e32 v23, v24, v222
	v_add_f32_e32 v7, v8, v223
	v_add_f32_e32 v24, v25, v224
	v_add_f32_e32 v8, v9, v225
	v_add_f32_e32 v25, v26, v226
	v_add_f32_e32 v9, v10, v227
	v_add_f32_e32 v26, v27, v228
	v_add_f32_e32 v10, v11, v229
	v_add_f32_e32 v27, v28, v230
	v_add_f32_e32 v11, v12, v231
	v_add_f32_e32 v28, v29, v232
	v_add_f32_e32 v12, v13, v233
	v_add_f32_e32 v29, v30, v234
	v_add_f32_e32 v13, v14, v235
	v_add_f32_e32 v30, v31, v236
	v_add_f32_e32 v14, v15, v237
	v_add_f32_e32 v31, v32, v238
	v_add_f32_e32 v15, v16, v239
	v_add_f32_e32 v32, v33, v240
	v_add_f32_e32 v16, v17, v241
	v_max3_f32 v17, v191, v44, v43
	v_lshlrev_b32_e32 v33, 7, v0
	v_max3_f32 v17, v17, v18, v2
	v_lshlrev_b32_e32 v45, 2, v85
	v_max3_f32 v17, v17, v19, v3
	s_movk_i32 s8, 0x80
	v_max3_f32 v17, v17, v20, v4
	v_bitop3_b32 v197, v33, s8, v45 bitop3:0x36
	v_max3_f32 v17, v17, v21, v5
	v_mov_b32_e32 v79, 0xf149f2ca
	v_max3_f32 v17, v17, v22, v6
	v_max3_f32 v17, v17, v23, v7
	v_max3_f32 v17, v17, v24, v8
	v_max3_f32 v17, v17, v25, v9
	v_max3_f32 v17, v17, v26, v10
	v_max3_f32 v17, v17, v27, v11
	v_max3_f32 v17, v17, v28, v12
	v_max3_f32 v17, v17, v29, v13
	v_max3_f32 v17, v17, v30, v14
	v_max3_f32 v17, v17, v31, v15
	v_max3_f32 v17, v17, v32, v16
	ds_bpermute_b32 v33, v197, v17
	v_max_f32_e32 v17, v17, v17
	s_waitcnt lgkmcnt(0)
	v_max_f32_e32 v33, v33, v33
	v_max_f32_e32 v17, v17, v33
	v_max_f32_e32 v75, 0xf149f2ca, v17
	v_sub_f32_e32 v5, v5, v75
	v_exp_f32_e32 v59, v5
	v_sub_f32_e32 v5, v22, v75
	v_exp_f32_e32 v22, v5
	v_sub_f32_e32 v5, v6, v75
	v_exp_f32_e32 v60, v5
	v_sub_f32_e32 v5, v23, v75
	v_exp_f32_e32 v23, v5
	v_sub_f32_e32 v5, v7, v75
	v_sub_f32_e32 v33, v44, v75
	v_sub_f32_e32 v43, v43, v75
	v_exp_f32_e32 v61, v5
	v_sub_f32_e32 v5, v24, v75
	v_exp_f32_e32 v33, v33
	v_exp_f32_e32 v43, v43
	v_sub_f32_e32 v18, v18, v75
	v_sub_f32_e32 v2, v2, v75
	v_sub_f32_e32 v3, v3, v75
	v_exp_f32_e32 v24, v5
	v_sub_f32_e32 v5, v8, v75
	v_exp_f32_e32 v18, v18
	v_exp_f32_e32 v56, v2
	v_sub_f32_e32 v19, v19, v75
	v_exp_f32_e32 v57, v3
	v_sub_f32_e32 v3, v20, v75
	v_exp_f32_e32 v62, v5
	v_sub_f32_e32 v5, v25, v75
	v_exp_f32_e32 v19, v19
	v_exp_f32_e32 v20, v3
	v_sub_f32_e32 v3, v4, v75
	v_exp_f32_e32 v63, v5
	v_sub_f32_e32 v5, v9, v75
	v_exp_f32_e32 v58, v3
	v_sub_f32_e32 v21, v21, v75
	v_exp_f32_e32 v64, v5
	v_sub_f32_e32 v5, v26, v75
	v_add_f32_e32 v44, v33, v43
	v_exp_f32_e32 v21, v21
	v_exp_f32_e32 v65, v5
	v_sub_f32_e32 v5, v10, v75
	v_add_f32_e32 v44, 0, v44
	v_add_f32_e32 v45, v18, v56
	v_exp_f32_e32 v66, v5
	v_sub_f32_e32 v5, v27, v75
	v_add_f32_e32 v3, v45, v44
	v_add_f32_e32 v4, v19, v57
	v_exp_f32_e32 v67, v5
	v_sub_f32_e32 v5, v11, v75
	v_add_f32_e32 v3, v4, v3
	v_add_f32_e32 v4, v20, v58
	v_exp_f32_e32 v68, v5
	v_sub_f32_e32 v5, v28, v75
	v_add_f32_e32 v3, v4, v3
	v_add_f32_e32 v4, v21, v59
	v_exp_f32_e32 v69, v5
	v_sub_f32_e32 v5, v12, v75
	v_add_f32_e32 v3, v4, v3
	v_add_f32_e32 v4, v22, v60
	v_exp_f32_e32 v70, v5
	v_sub_f32_e32 v5, v29, v75
	v_add_f32_e32 v3, v4, v3
	v_add_f32_e32 v4, v23, v61
	v_exp_f32_e32 v71, v5
	v_sub_f32_e32 v5, v13, v75
	v_add_f32_e32 v3, v4, v3
	v_add_f32_e32 v4, v24, v62
	v_exp_f32_e32 v72, v5
	v_sub_f32_e32 v5, v30, v75
	v_add_f32_e32 v3, v4, v3
	v_add_f32_e32 v4, v63, v64
	v_exp_f32_e32 v73, v5
	v_sub_f32_e32 v5, v14, v75
	v_add_f32_e32 v3, v4, v3
	v_add_f32_e32 v4, v65, v66
	v_exp_f32_e32 v80, v5
	v_add_f32_e32 v3, v4, v3
	v_add_f32_e32 v4, v67, v68
	v_add_f32_e32 v3, v4, v3
	v_add_f32_e32 v4, v69, v70
	v_add_f32_e32 v3, v4, v3
	v_add_f32_e32 v4, v71, v72
	v_add_f32_e32 v3, v4, v3
	v_add_f32_e32 v4, v73, v80
	v_add_f32_e32 v3, v4, v3
	v_sub_f32_e32 v4, v31, v75
	v_exp_f32_e32 v81, v4
	v_sub_f32_e32 v4, v15, v75
	v_exp_f32_e32 v90, v4
	v_sub_f32_e32 v4, v32, v75
	v_exp_f32_e32 v91, v4
	v_sub_f32_e32 v4, v16, v75
	v_exp_f32_e32 v92, v4
	v_sub_f32_e32 v2, 0xf149f2ca, v75
	v_add_f32_e32 v4, v81, v90
	v_add_f32_e32 v3, v4, v3
	v_exp_f32_e32 v2, v2
	v_add_f32_e32 v4, v91, v92
	v_add_f32_e32 v76, v4, v3
	ds_bpermute_b32 v77, v197, v76
	v_cmp_gt_f32_e32 vcc, v17, v79
	s_cmp_lg_u64 vcc, 0
	v_mul_f32_e32 v78, 0, v2
	s_cselect_b64 vcc, -1, 0
	v_cndmask_b32_e32 v2, 0, v78, vcc
	v_mov_b32_e32 v3, v2
	v_mov_b32_e32 v4, v2
	v_mov_b32_e32 v5, v2
	v_mov_b32_e32 v6, v2
	v_mov_b32_e32 v7, v2
	v_mov_b32_e32 v8, v2
	v_mov_b32_e32 v9, v2
	v_mov_b32_e32 v10, v2
	v_mov_b32_e32 v11, v2
	v_mov_b32_e32 v12, v2
	v_mov_b32_e32 v13, v2
	v_mov_b32_e32 v14, v2
	v_mov_b32_e32 v15, v2
	v_mov_b32_e32 v16, v2
	v_mov_b32_e32 v17, v2
	ds_read_b64_tr_b16 v[44:45], v89 offset:12288
	ds_read_b64_tr_b16 v[46:47], v89 offset:13824
	ds_read_b64_tr_b16 v[50:51], v89 offset:13888
	ds_read_b64_tr_b16 v[48:49], v89 offset:12352
	v_cvt_pk_bf16_f32 v52, v33, v18
	v_cvt_pk_bf16_f32 v53, v19, v20
	v_cvt_pk_bf16_f32 v54, v21, v22
	v_cvt_pk_bf16_f32 v55, v23, v24
	s_nop 1
	v_mfma_f32_32x32x16_bf16 v[18:33], v[34:37], v[52:55], v[2:17]
	v_mfma_f32_32x32x16_bf16 v[2:17], v[38:41], v[52:55], v[2:17]
	ds_read_b64_tr_b16 v[34:35], v89 offset:15360
	ds_read_b64_tr_b16 v[36:37], v89 offset:16896
	ds_read_b64_tr_b16 v[40:41], v89 offset:16960
	ds_read_b64_tr_b16 v[38:39], v89 offset:15424
	v_cvt_pk_bf16_f32 v52, v63, v65
	v_cvt_pk_bf16_f32 v53, v67, v69
	v_cvt_pk_bf16_f32 v54, v71, v73
	v_cvt_pk_bf16_f32 v55, v81, v91
	s_waitcnt lgkmcnt(6)
	s_nop 0
	v_mfma_f32_32x32x16_bf16 v[18:33], v[44:47], v[52:55], v[18:33]
	s_waitcnt lgkmcnt(4)
	v_mfma_f32_32x32x16_bf16 v[2:17], v[48:51], v[52:55], v[2:17]
	ds_read_b64_tr_b16 v[44:45], v89 offset:18432
	ds_read_b64_tr_b16 v[46:47], v89 offset:19968
	ds_read_b64_tr_b16 v[50:51], v89 offset:20032
	ds_read_b64_tr_b16 v[48:49], v89 offset:18496
	v_cvt_pk_bf16_f32 v52, v43, v56
	v_cvt_pk_bf16_f32 v53, v57, v58
	v_cvt_pk_bf16_f32 v54, v59, v60
	v_cvt_pk_bf16_f32 v55, v61, v62
	s_waitcnt lgkmcnt(6)
	s_nop 0
	v_mfma_f32_32x32x16_bf16 v[18:33], v[34:37], v[52:55], v[18:33]
	s_waitcnt lgkmcnt(4)
	v_mfma_f32_32x32x16_bf16 v[2:17], v[38:41], v[52:55], v[2:17]
	v_cvt_pk_bf16_f32 v34, v64, v66
	v_cvt_pk_bf16_f32 v35, v68, v70
	v_cvt_pk_bf16_f32 v36, v72, v80
	v_cvt_pk_bf16_f32 v37, v90, v92
	s_waitcnt lgkmcnt(2)
	s_nop 0
	v_mfma_f32_32x32x16_bf16 v[18:33], v[44:47], v[34:37], v[18:33]
	s_waitcnt lgkmcnt(0)
	v_mfma_f32_32x32x16_bf16 v[2:17], v[48:51], v[34:37], v[2:17]
	ds_read_b128 v[34:37], v42 offset:21504
	ds_read_b128 v[66:69], v42 offset:21536
	ds_read_b128 v[38:41], v42 offset:26112
	ds_read_b128 v[70:73], v42 offset:26144
	ds_read_b128 v[90:93], v42 offset:21568
	ds_read_b128 v[94:97], v42 offset:21600
	ds_read_b128 v[114:117], v42 offset:26176
	ds_read_b128 v[118:121], v42 offset:26208
	s_waitcnt lgkmcnt(7)
	v_mfma_f32_32x32x16_bf16 v[50:65], v[34:37], v[98:101], 0
	s_waitcnt lgkmcnt(5)
	v_mfma_f32_32x32x16_bf16 v[34:49], v[38:41], v[98:101], 0
	v_mfma_f32_32x32x16_bf16 v[50:65], v[66:69], v[102:105], v[50:65]
	s_waitcnt lgkmcnt(4)
	v_mfma_f32_32x32x16_bf16 v[34:49], v[70:73], v[102:105], v[34:49]
	s_waitcnt lgkmcnt(3)
	v_mfma_f32_32x32x16_bf16 v[50:65], v[90:93], v[106:109], v[50:65]
	ds_read_b64_tr_b16 v[66:67], v89 offset:30720
	ds_read_b64_tr_b16 v[68:69], v89 offset:32256
	ds_read_b64_tr_b16 v[72:73], v89 offset:32320
	ds_read_b64_tr_b16 v[70:71], v89 offset:30784
	v_add_u32_e32 v81, 0xfffffbe1, v74
	v_cmp_lt_i32_e64 s[8:9], -1, v81
	v_cmp_gt_i32_e32 vcc, 16, v0
	s_and_b64 s[10:11], vcc, s[8:9]
	v_mov_b32_e32 v80, 0xf149f2ca
	s_waitcnt lgkmcnt(5)
	v_mfma_f32_32x32x16_bf16 v[34:49], v[114:117], v[106:109], v[34:49]
	v_mfma_f32_32x32x16_bf16 v[50:65], v[94:97], v[110:113], v[50:65]
	s_waitcnt lgkmcnt(4)
	v_mfma_f32_32x32x16_bf16 v[34:49], v[118:121], v[110:113], v[34:49]
	v_min_u32_e32 v210, 0x7f, v81
	v_lshl_add_u32 v210, v210, 2, s3
	v_cndmask_b32_e64 v210, v242, v210, s[10:11]
	ds_read_b32 v210, v210
	s_nop 6
	v_add_u32_e32 v150, 0xfffff9e1, v74
	v_cmp_lt_i32_e64 s[10:11], -1, v150
	v_cmp_gt_i32_e64 s[8:9], 8, v0
	s_and_b64 s[12:13], s[8:9], s[10:11]
	v_min_u32_e32 v211, 0x7f, v150
	v_lshl_add_u32 v211, v211, 2, s3
	v_cndmask_b32_e64 v211, v242, v211, s[12:13]
	ds_read_b32 v211, v211
	v_add_u32_e32 v81, 0xfffffbd1, v74
	v_cmp_lt_i32_e64 s[10:11], -1, v81
	s_and_b64 s[12:13], vcc, s[10:11]
	v_min_u32_e32 v212, 0x7f, v81
	v_lshl_add_u32 v212, v212, 2, s3
	v_cndmask_b32_e64 v212, v242, v212, s[12:13]
	ds_read_b32 v212, v212
	v_add_u32_e32 v151, 0xfffff9d1, v74
	v_cmp_lt_i32_e64 s[10:11], -1, v151
	s_and_b64 s[12:13], s[8:9], s[10:11]
	v_min_u32_e32 v213, 0x7f, v151
	v_lshl_add_u32 v213, v213, 2, s3
	v_cndmask_b32_e64 v213, v242, v213, s[12:13]
	ds_read_b32 v213, v213
	v_add_u32_e32 v81, 0xfffffbc1, v74
	v_cmp_lt_i32_e64 s[10:11], -1, v81
	s_and_b64 s[12:13], vcc, s[10:11]
	v_min_u32_e32 v214, 0x7f, v81
	v_lshl_add_u32 v214, v214, 2, s3
	v_cndmask_b32_e64 v214, v242, v214, s[12:13]
	ds_read_b32 v214, v214
	v_add_u32_e32 v152, 0xfffff9c1, v74
	v_cmp_lt_i32_e32 vcc, -1, v152
	s_and_b64 s[10:11], s[8:9], vcc
	v_min_u32_e32 v215, 0x7f, v152
	v_lshl_add_u32 v215, v215, 2, s3
	v_cndmask_b32_e64 v215, v242, v215, s[10:11]
	ds_read_b32 v215, v215
	v_add_u32_e32 v81, 0xfffffbb1, v74
	v_cmp_lt_i32_e32 vcc, -1, v81
	v_cmp_gt_i32_e64 s[8:9], 15, v0
	s_and_b64 s[10:11], s[8:9], vcc
	v_min_u32_e32 v216, 0x7f, v81
	v_lshl_add_u32 v216, v216, 2, s3
	v_cndmask_b32_e64 v216, v242, v216, s[10:11]
	ds_read_b32 v216, v216
	v_add_u32_e32 v153, 0xfffff9b1, v74
	v_cmp_lt_i32_e32 vcc, -1, v153
	v_cmp_gt_i32_e64 s[8:9], 7, v0
	s_and_b64 s[10:11], s[8:9], vcc
	v_min_u32_e32 v217, 0x7f, v153
	v_lshl_add_u32 v217, v217, 2, s3
	v_cndmask_b32_e64 v217, v242, v217, s[10:11]
	ds_read_b32 v217, v217
	v_add_u32_e32 v81, 0xfffffb61, v74
	v_cmp_lt_i32_e64 s[8:9], -1, v81
	v_cmp_gt_i32_e32 vcc, 14, v0
	s_and_b64 s[10:11], vcc, s[8:9]
	v_min_u32_e32 v218, 0x7f, v81
	v_lshl_add_u32 v218, v218, 2, s3
	v_cndmask_b32_e64 v218, v242, v218, s[10:11]
	ds_read_b32 v218, v218
	v_add_u32_e32 v154, 0xfffff961, v74
	v_cmp_lt_i32_e64 s[10:11], -1, v154
	v_cmp_gt_i32_e64 s[8:9], 6, v0
	s_and_b64 s[12:13], s[8:9], s[10:11]
	v_min_u32_e32 v219, 0x7f, v154
	v_lshl_add_u32 v219, v219, 2, s3
	v_cndmask_b32_e64 v219, v242, v219, s[12:13]
	ds_read_b32 v219, v219
	v_add_u32_e32 v81, 0xfffffb51, v74
	v_cmp_lt_i32_e64 s[10:11], -1, v81
	s_and_b64 s[12:13], vcc, s[10:11]
	v_min_u32_e32 v220, 0x7f, v81
	v_lshl_add_u32 v220, v220, 2, s3
	v_cndmask_b32_e64 v220, v242, v220, s[12:13]
	ds_read_b32 v220, v220
	v_add_u32_e32 v155, 0xfffff951, v74
	v_cmp_lt_i32_e64 s[10:11], -1, v155
	s_and_b64 s[12:13], s[8:9], s[10:11]
	v_min_u32_e32 v221, 0x7f, v155
	v_lshl_add_u32 v221, v221, 2, s3
	v_cndmask_b32_e64 v221, v242, v221, s[12:13]
	ds_read_b32 v221, v221
	v_add_u32_e32 v81, 0xfffffb41, v74
	v_cmp_lt_i32_e64 s[10:11], -1, v81
	s_and_b64 s[12:13], vcc, s[10:11]
	v_min_u32_e32 v222, 0x7f, v81
	v_lshl_add_u32 v222, v222, 2, s3
	v_cndmask_b32_e64 v222, v242, v222, s[12:13]
	ds_read_b32 v222, v222
	v_add_u32_e32 v156, 0xfffff941, v74
	v_cmp_lt_i32_e32 vcc, -1, v156
	s_and_b64 s[10:11], s[8:9], vcc
	v_min_u32_e32 v223, 0x7f, v156
	v_lshl_add_u32 v223, v223, 2, s3
	v_cndmask_b32_e64 v223, v242, v223, s[10:11]
	ds_read_b32 v223, v223
	v_add_u32_e32 v81, 0xfffffb31, v74
	v_cmp_lt_i32_e32 vcc, -1, v81
	v_cmp_gt_i32_e64 s[8:9], 13, v0
	s_and_b64 s[10:11], s[8:9], vcc
	v_min_u32_e32 v224, 0x7f, v81
	v_lshl_add_u32 v224, v224, 2, s3
	v_cndmask_b32_e64 v224, v242, v224, s[10:11]
	ds_read_b32 v224, v224
	v_add_u32_e32 v157, 0xfffff931, v74
	v_cmp_lt_i32_e32 vcc, -1, v157
	v_cmp_gt_i32_e64 s[8:9], 5, v0
	s_and_b64 s[10:11], s[8:9], vcc
	v_min_u32_e32 v225, 0x7f, v157
	v_lshl_add_u32 v225, v225, 2, s3
	v_cndmask_b32_e64 v225, v242, v225, s[10:11]
	ds_read_b32 v225, v225
	v_add_u32_e32 v81, 0xfffffae1, v74
	v_cmp_lt_i32_e64 s[8:9], -1, v81
	v_cmp_gt_i32_e32 vcc, 12, v0
	s_and_b64 s[10:11], vcc, s[8:9]
	v_min_u32_e32 v226, 0x7f, v81
	v_lshl_add_u32 v226, v226, 2, s3
	v_cndmask_b32_e64 v226, v242, v226, s[10:11]
	ds_read_b32 v226, v226
	v_add_u32_e32 v158, 0xfffff8e1, v74
	v_cmp_lt_i32_e64 s[10:11], -1, v158
	v_cmp_gt_i32_e64 s[8:9], 4, v0
	s_and_b64 s[12:13], s[8:9], s[10:11]
	v_min_u32_e32 v227, 0x7f, v158
	v_lshl_add_u32 v227, v227, 2, s3
	v_cndmask_b32_e64 v227, v242, v227, s[12:13]
	ds_read_b32 v227, v227
	v_add_u32_e32 v81, 0xfffffad1, v74
	v_cmp_lt_i32_e64 s[10:11], -1, v81
	s_and_b64 s[12:13], vcc, s[10:11]
	v_min_u32_e32 v228, 0x7f, v81
	v_lshl_add_u32 v228, v228, 2, s3
	v_cndmask_b32_e64 v228, v242, v228, s[12:13]
	ds_read_b32 v228, v228
	v_add_u32_e32 v159, 0xfffff8d1, v74
	v_cmp_lt_i32_e64 s[10:11], -1, v159
	s_and_b64 s[12:13], s[8:9], s[10:11]
	v_min_u32_e32 v229, 0x7f, v159
	v_lshl_add_u32 v229, v229, 2, s3
	v_cndmask_b32_e64 v229, v242, v229, s[12:13]
	ds_read_b32 v229, v229
	v_add_u32_e32 v81, 0xfffffac1, v74
	v_cmp_lt_i32_e64 s[10:11], -1, v81
	s_and_b64 s[12:13], vcc, s[10:11]
	v_min_u32_e32 v230, 0x7f, v81
	v_lshl_add_u32 v230, v230, 2, s3
	v_cndmask_b32_e64 v230, v242, v230, s[12:13]
	ds_read_b32 v230, v230
	v_add_u32_e32 v160, 0xfffff8c1, v74
	v_cmp_lt_i32_e32 vcc, -1, v160
	s_and_b64 s[10:11], s[8:9], vcc
	v_min_u32_e32 v231, 0x7f, v160
	v_lshl_add_u32 v231, v231, 2, s3
	v_cndmask_b32_e64 v231, v242, v231, s[10:11]
	ds_read_b32 v231, v231
	v_add_u32_e32 v81, 0xfffffab1, v74
	v_cmp_lt_i32_e32 vcc, -1, v81
	v_cmp_gt_i32_e64 s[8:9], 11, v0
	s_and_b64 s[10:11], s[8:9], vcc
	v_min_u32_e32 v232, 0x7f, v81
	v_lshl_add_u32 v232, v232, 2, s3
	v_cndmask_b32_e64 v232, v242, v232, s[10:11]
	ds_read_b32 v232, v232
	v_add_u32_e32 v161, 0xfffff8b1, v74
	v_cmp_lt_i32_e32 vcc, -1, v161
	v_cmp_gt_i32_e64 s[8:9], 3, v0
	s_and_b64 s[10:11], s[8:9], vcc
	v_min_u32_e32 v233, 0x7f, v161
	v_lshl_add_u32 v233, v233, 2, s3
	v_cndmask_b32_e64 v233, v242, v233, s[10:11]
	ds_read_b32 v233, v233
	v_add_u32_e32 v81, 0xfffffa61, v74
	v_cmp_lt_i32_e64 s[8:9], -1, v81
	v_cmp_gt_i32_e32 vcc, 10, v0
	s_and_b64 s[10:11], vcc, s[8:9]
	v_min_u32_e32 v234, 0x7f, v81
	v_lshl_add_u32 v234, v234, 2, s3
	v_cndmask_b32_e64 v234, v242, v234, s[10:11]
	ds_read_b32 v234, v234
	v_add_u32_e32 v162, 0xfffff861, v74
	v_cmp_lt_i32_e64 s[10:11], -1, v162
	v_cmp_gt_i32_e64 s[8:9], 2, v0
	s_and_b64 s[12:13], s[8:9], s[10:11]
	v_min_u32_e32 v235, 0x7f, v162
	v_lshl_add_u32 v235, v235, 2, s3
	v_cndmask_b32_e64 v235, v242, v235, s[12:13]
	ds_read_b32 v235, v235
	v_add_u32_e32 v81, 0xfffffa51, v74
	v_cmp_lt_i32_e64 s[10:11], -1, v81
	s_and_b64 s[12:13], vcc, s[10:11]
	v_min_u32_e32 v236, 0x7f, v81
	v_lshl_add_u32 v236, v236, 2, s3
	v_cndmask_b32_e64 v236, v242, v236, s[12:13]
	ds_read_b32 v236, v236
	v_add_u32_e32 v163, 0xfffff851, v74
	v_cmp_lt_i32_e64 s[10:11], -1, v163
	s_and_b64 s[12:13], s[8:9], s[10:11]
	v_min_u32_e32 v237, 0x7f, v163
	v_lshl_add_u32 v237, v237, 2, s3
	v_cndmask_b32_e64 v237, v242, v237, s[12:13]
	ds_read_b32 v237, v237
	v_add_u32_e32 v81, 0xfffffa41, v74
	v_cmp_lt_i32_e64 s[10:11], -1, v81
	s_and_b64 s[12:13], vcc, s[10:11]
	v_min_u32_e32 v238, 0x7f, v81
	v_lshl_add_u32 v238, v238, 2, s3
	v_cndmask_b32_e64 v238, v242, v238, s[12:13]
	ds_read_b32 v238, v238
	v_add_u32_e32 v164, 0xfffff841, v74
	v_cmp_lt_i32_e32 vcc, -1, v164
	s_and_b64 s[10:11], s[8:9], vcc
	v_min_u32_e32 v239, 0x7f, v164
	v_lshl_add_u32 v239, v239, 2, s3
	v_cndmask_b32_e64 v239, v242, v239, s[10:11]
	ds_read_b32 v239, v239
	v_add_u32_e32 v81, 0xfffffa31, v74
	v_cmp_lt_i32_e32 vcc, -1, v81
	v_cmp_gt_i32_e64 s[8:9], 9, v0
	s_and_b64 s[10:11], s[8:9], vcc
	v_min_u32_e32 v240, 0x7f, v81
	v_lshl_add_u32 v240, v240, 2, s3
	v_cndmask_b32_e64 v240, v242, v240, s[10:11]
	ds_read_b32 v240, v240
	v_add_u32_e32 v165, 0xfffff831, v74
	v_cmp_lt_i32_e32 vcc, -1, v165
	v_cmp_gt_i32_e64 s[8:9], 1, v0
	s_and_b64 s[10:11], s[8:9], vcc
	v_min_u32_e32 v241, 0x7f, v165
	v_lshl_add_u32 v241, v241, 2, s3
	v_cndmask_b32_e64 v241, v242, v241, s[10:11]
	ds_read_b32 v241, v241
	s_waitcnt lgkmcnt(0)
	v_add_f32_e32 v80, v50, v210
	v_add_f32_e32 v79, v34, v211
	v_add_f32_e32 v50, v51, v212
	v_add_f32_e32 v34, v35, v213
	v_add_f32_e32 v51, v52, v214
	v_add_f32_e32 v35, v36, v215
	v_add_f32_e32 v52, v53, v216
	v_add_f32_e32 v36, v37, v217
	v_add_f32_e32 v53, v54, v218
	v_add_f32_e32 v37, v38, v219
	v_add_f32_e32 v54, v55, v220
	v_add_f32_e32 v38, v39, v221
	v_add_f32_e32 v55, v56, v222
	v_add_f32_e32 v39, v40, v223
	v_add_f32_e32 v56, v57, v224
	v_add_f32_e32 v40, v41, v225
	v_add_f32_e32 v57, v58, v226
	v_add_f32_e32 v41, v42, v227
	v_add_f32_e32 v58, v59, v228
	v_add_f32_e32 v42, v43, v229
	v_add_f32_e32 v59, v60, v230
	v_add_f32_e32 v43, v44, v231
	v_add_f32_e32 v60, v61, v232
	v_add_f32_e32 v44, v45, v233
	v_add_f32_e32 v61, v62, v234
	v_add_f32_e32 v45, v46, v235
	v_add_f32_e32 v62, v63, v236
	v_add_f32_e32 v46, v47, v237
	v_add_f32_e32 v63, v64, v238
	v_add_f32_e32 v47, v48, v239
	v_add_f32_e32 v64, v65, v240
	v_add_f32_e32 v48, v49, v241
	v_max3_f32 v0, v191, v80, v79
	v_max_f32_e32 v65, v75, v75
	v_max3_f32 v0, v0, v50, v34
	v_max3_f32 v0, v0, v51, v35
	v_max3_f32 v0, v0, v52, v36
	v_max3_f32 v0, v0, v53, v37
	v_max3_f32 v0, v0, v54, v38
	v_max3_f32 v0, v0, v55, v39
	v_max3_f32 v0, v0, v56, v40
	v_max3_f32 v0, v0, v57, v41
	v_max3_f32 v0, v0, v58, v42
	v_max3_f32 v0, v0, v59, v43
	v_max3_f32 v0, v0, v60, v44
	v_max3_f32 v0, v0, v61, v45
	v_max3_f32 v0, v0, v62, v46
	v_max3_f32 v0, v0, v63, v47
	v_max3_f32 v0, v0, v64, v48
	ds_bpermute_b32 v49, v197, v0
	v_max_f32_e32 v0, v0, v0
	s_waitcnt lgkmcnt(0)
	v_max_f32_e32 v49, v49, v49
	v_max_f32_e32 v49, v0, v49
	v_max_f32_e32 v118, v65, v49
	v_sub_f32_e32 v35, v35, v118
	v_exp_f32_e32 v92, v35
	v_sub_f32_e32 v35, v52, v118
	v_exp_f32_e32 v125, v35
	v_sub_f32_e32 v35, v36, v118
	v_sub_f32_e32 v36, v53, v118
	v_exp_f32_e32 v136, v36
	v_sub_f32_e32 v36, v37, v118
	v_exp_f32_e32 v94, v36
	v_sub_f32_e32 v36, v54, v118
	v_exp_f32_e32 v138, v36
	v_sub_f32_e32 v36, v38, v118
	v_exp_f32_e32 v95, v36
	v_sub_f32_e32 v36, v55, v118
	v_exp_f32_e32 v141, v36
	v_sub_f32_e32 v36, v39, v118
	v_exp_f32_e32 v96, v36
	v_sub_f32_e32 v36, v56, v118
	v_sub_f32_e32 v0, v80, v118
	v_exp_f32_e32 v142, v36
	v_sub_f32_e32 v36, v40, v118
	v_sub_f32_e32 v65, v79, v118
	v_exp_f32_e32 v116, v0
	v_sub_f32_e32 v0, v50, v118
	v_exp_f32_e32 v97, v36
	v_sub_f32_e32 v36, v57, v118
	v_exp_f32_e32 v90, v65
	v_exp_f32_e32 v119, v0
	v_sub_f32_e32 v0, v34, v118
	v_exp_f32_e32 v120, v36
	v_sub_f32_e32 v36, v41, v118
	v_exp_f32_e32 v91, v0
	v_sub_f32_e32 v51, v51, v118
	v_exp_f32_e32 v114, v36
	v_sub_f32_e32 v36, v58, v118
	v_exp_f32_e32 v123, v51
	v_exp_f32_e32 v122, v36
	v_sub_f32_e32 v36, v42, v118
	v_exp_f32_e32 v93, v35
	v_exp_f32_e32 v115, v36
	v_sub_f32_e32 v36, v59, v118
	v_add_f32_e32 v34, v116, v90
	v_exp_f32_e32 v126, v36
	v_sub_f32_e32 v36, v43, v118
	v_add_f32_e32 v34, 0, v34
	v_add_f32_e32 v50, v119, v91
	v_exp_f32_e32 v117, v36
	v_sub_f32_e32 v36, v60, v118
	v_add_f32_e32 v34, v50, v34
	v_add_f32_e32 v35, v123, v92
	v_exp_f32_e32 v128, v36
	v_sub_f32_e32 v36, v44, v118
	v_add_f32_e32 v34, v35, v34
	v_add_f32_e32 v35, v125, v93
	v_exp_f32_e32 v121, v36
	v_sub_f32_e32 v36, v61, v118
	v_add_f32_e32 v34, v35, v34
	v_add_f32_e32 v35, v136, v94
	v_exp_f32_e32 v139, v36
	v_sub_f32_e32 v36, v45, v118
	v_add_f32_e32 v34, v35, v34
	v_add_f32_e32 v35, v138, v95
	v_exp_f32_e32 v124, v36
	v_sub_f32_e32 v36, v62, v118
	v_add_f32_e32 v34, v35, v34
	v_add_f32_e32 v35, v141, v96
	v_exp_f32_e32 v140, v36
	v_sub_f32_e32 v36, v46, v118
	v_add_f32_e32 v34, v35, v34
	v_add_f32_e32 v35, v142, v97
	v_exp_f32_e32 v127, v36
	v_sub_f32_e32 v36, v63, v118
	v_add_f32_e32 v34, v35, v34
	v_add_f32_e32 v35, v120, v114
	v_exp_f32_e32 v143, v36
	v_sub_f32_e32 v36, v47, v118
	v_add_f32_e32 v34, v35, v34
	v_add_f32_e32 v35, v122, v115
	v_exp_f32_e32 v129, v36
	v_sub_f32_e32 v36, v64, v118
	v_add_f32_e32 v34, v35, v34
	v_add_f32_e32 v35, v126, v117
	v_exp_f32_e32 v144, v36
	v_sub_f32_e32 v36, v48, v118
	v_add_f32_e32 v34, v35, v34
	v_add_f32_e32 v35, v128, v121
	v_exp_f32_e32 v137, v36
	v_add_f32_e32 v34, v35, v34
	v_add_f32_e32 v35, v139, v124
	v_add_f32_e32 v34, v35, v34
	v_add_f32_e32 v35, v140, v127
	v_add_f32_e32 v34, v35, v34
	v_add_f32_e32 v35, v143, v129
	v_add_f32_e32 v34, v35, v34
	v_add_f32_e32 v35, v144, v137
	v_add_f32_e32 v34, v35, v34
	v_sub_f32_e32 v0, v75, v118
	ds_bpermute_b32 v35, v197, v34
	v_exp_f32_e32 v0, v0
	v_cmp_gt_f32_e32 vcc, v49, v75
	s_cbranch_vccz .LBB0_1382
	v_pk_mul_f32 v[32:33], v[32:33], v[0:1] op_sel_hi:[1,0]
	v_pk_mul_f32 v[30:31], v[30:31], v[0:1] op_sel_hi:[1,0]
	v_pk_mul_f32 v[28:29], v[28:29], v[0:1] op_sel_hi:[1,0]
	v_pk_mul_f32 v[26:27], v[26:27], v[0:1] op_sel_hi:[1,0]
	v_pk_mul_f32 v[24:25], v[24:25], v[0:1] op_sel_hi:[1,0]
	v_pk_mul_f32 v[22:23], v[22:23], v[0:1] op_sel_hi:[1,0]
	v_pk_mul_f32 v[20:21], v[20:21], v[0:1] op_sel_hi:[1,0]
	v_pk_mul_f32 v[18:19], v[18:19], v[0:1] op_sel_hi:[1,0]
	v_pk_mul_f32 v[16:17], v[16:17], v[0:1] op_sel_hi:[1,0]
	v_pk_mul_f32 v[14:15], v[14:15], v[0:1] op_sel_hi:[1,0]
	v_pk_mul_f32 v[12:13], v[12:13], v[0:1] op_sel_hi:[1,0]
	v_pk_mul_f32 v[10:11], v[10:11], v[0:1] op_sel_hi:[1,0]
	v_pk_mul_f32 v[8:9], v[8:9], v[0:1] op_sel_hi:[1,0]
	v_pk_mul_f32 v[6:7], v[6:7], v[0:1] op_sel_hi:[1,0]
	v_pk_mul_f32 v[4:5], v[4:5], v[0:1] op_sel_hi:[1,0]
	v_pk_mul_f32 v[2:3], v[2:3], v[0:1] op_sel_hi:[1,0]

.LBB0_1416:
	v_cvt_pk_bf16_f32 v34, v116, v119
	v_cvt_pk_bf16_f32 v35, v123, v125
	v_cvt_pk_bf16_f32 v36, v136, v138
	v_cvt_pk_bf16_f32 v37, v141, v142
	s_mov_b32 s71, s67
	s_movk_i32 s8, 0x1000
	v_mfma_f32_32x32x16_bf16 v[18:33], v[66:69], v[34:37], v[18:33]
	v_cvt_pk_bf16_f32 v38, v114, v115
	v_cvt_pk_bf16_f32 v39, v117, v121
	v_cvt_pk_bf16_f32 v40, v124, v127
	v_cvt_pk_bf16_f32 v41, v129, v137
	v_lshl_add_u32 v200, v87, 2, 0
	v_add_u32_e32 v199, 0xa800, v200
	s_add_i32 s17, 0, 0x1c000
	v_mfma_f32_32x32x16_bf16 v[2:17], v[70:73], v[34:37], v[2:17]
	v_cvt_pk_bf16_f32 v34, v120, v122
	v_cvt_pk_bf16_f32 v35, v126, v128
	v_cvt_pk_bf16_f32 v36, v139, v140
	v_cvt_pk_bf16_f32 v37, v143, v144
	s_nop 1
	v_mfma_f32_32x32x16_bf16 v[18:33], v[74:77], v[34:37], v[18:33]
	v_mfma_f32_32x32x16_bf16 v[2:17], v[78:81], v[34:37], v[2:17]
	v_cvt_pk_bf16_f32 v34, v90, v91
	v_cvt_pk_bf16_f32 v35, v92, v93
	v_cvt_pk_bf16_f32 v36, v94, v95
	v_cvt_pk_bf16_f32 v37, v96, v97
	s_nop 1
	v_mfma_f32_32x32x16_bf16 v[18:33], v[62:65], v[34:37], v[18:33]
	v_mfma_f32_32x32x16_bf16 v[2:17], v[58:61], v[34:37], v[2:17]
	v_lshl_add_u64 v[34:35], v[82:83], 0, s[70:71]
	v_add_co_u32_e32 v36, vcc, s8, v34
	s_nop 1
	v_addc_co_u32_e32 v37, vcc, 0, v35, vcc
	v_mfma_f32_32x32x16_bf16 v[18:33], v[54:57], v[38:41], v[18:33]
	s_waitcnt vmcnt(0)
	v_add_u32_e32 v249, 0x21300, v200
	ds_write_b32 v249, v248
	v_lshlrev_b32_e32 v36, 16, v246
	v_mul_f32_e32 v36, 0xbfb8aa3b, v36
	v_exp_f32_e32 v36, v36
	v_mfma_f32_32x32x16_bf16 v[2:17], v[50:53], v[38:41], v[2:17]
	s_nop 6
	v_mul_f32_e64 v32, v0, v32
	v_mul_f32_e64 v33, v0, v33
	v_mul_f32_e64 v30, v0, v30
	v_mul_f32_e64 v31, v0, v31
	v_add_f32_e32 v36, 1.0, v36
	v_div_scale_f32 v37, s[8:9], v36, v36, 1.0
	v_rcp_f32_e32 v38, v37
	v_pk_mul_f32 v[28:29], v[0:1], v[28:29] op_sel_hi:[0,1]
	v_pk_mul_f32 v[26:27], v[0:1], v[26:27] op_sel_hi:[0,1]
	v_pk_mul_f32 v[24:25], v[0:1], v[24:25] op_sel_hi:[0,1]
	v_fma_f32 v39, -v37, v38, 1.0
	v_pk_mul_f32 v[22:23], v[0:1], v[22:23] op_sel_hi:[0,1]
	v_pk_mul_f32 v[20:21], v[0:1], v[20:21] op_sel_hi:[0,1]
	v_pk_mul_f32 v[18:19], v[0:1], v[18:19] op_sel_hi:[0,1]
	v_pk_mul_f32 v[16:17], v[0:1], v[16:17] op_sel_hi:[0,1]
	v_pk_mul_f32 v[14:15], v[0:1], v[14:15] op_sel_hi:[0,1]
	v_pk_mul_f32 v[12:13], v[0:1], v[12:13] op_sel_hi:[0,1]
	v_pk_mul_f32 v[10:11], v[0:1], v[10:11] op_sel_hi:[0,1]
	v_pk_mul_f32 v[8:9], v[0:1], v[8:9] op_sel_hi:[0,1]
	v_pk_mul_f32 v[6:7], v[0:1], v[6:7] op_sel_hi:[0,1]
	v_pk_mul_f32 v[4:5], v[0:1], v[4:5] op_sel_hi:[0,1]
	v_pk_mul_f32 v[2:3], v[0:1], v[2:3] op_sel_hi:[0,1]
	v_div_scale_f32 v0, vcc, 1.0, v36, 1.0
	v_fmac_f32_e32 v38, v39, v38
	v_mul_f32_e32 v39, v0, v38
	v_fma_f32 v40, -v37, v39, v0
	v_fmac_f32_e32 v39, v40, v38
	v_fma_f32 v0, -v37, v39, v0
	v_div_fmas_f32 v0, v0, v38, v39
	v_div_fixup_f32 v0, v0, v36, 1.0
	v_mul_f32_e32 v18, v18, v0
	v_mul_f32_e32 v19, v19, v0
	v_mul_f32_e32 v3, v3, v0
	v_mul_f32_e32 v5, v5, v0
	v_mul_f32_e32 v20, v20, v0
	v_mul_f32_e32 v4, v4, v0
	v_mul_f32_e32 v21, v21, v0
	v_mul_f32_e32 v22, v22, v0
	v_mul_f32_e32 v6, v6, v0
	v_mul_f32_e32 v23, v23, v0
	v_mul_f32_e32 v7, v7, v0
	v_mul_f32_e32 v24, v24, v0
	v_mul_f32_e32 v8, v8, v0
	v_mul_f32_e32 v25, v25, v0
	v_mul_f32_e32 v9, v9, v0
	v_mul_f32_e32 v26, v26, v0
	v_mul_f32_e32 v10, v10, v0
	v_mul_f32_e32 v27, v27, v0
	v_mul_f32_e32 v11, v11, v0
	v_mul_f32_e32 v28, v28, v0
	v_mul_f32_e32 v12, v12, v0
	v_mul_f32_e32 v29, v29, v0
	v_mul_f32_e32 v13, v13, v0
	v_mul_f32_e32 v30, v30, v0
	v_mul_f32_e32 v14, v14, v0
	ds_write2st64_b32 v200, v18, v19 offset0:168 offset1:176
	ds_write2st64_b32 v199, v3, v4 offset0:136 offset1:144
	ds_write2st64_b32 v200, v20, v21 offset0:184 offset1:192
	ds_write2st64_b32 v199, v5, v6 offset0:152 offset1:160
	ds_write2st64_b32 v200, v22, v23 offset0:200 offset1:208
	ds_write2st64_b32 v199, v7, v8 offset0:168 offset1:176
	ds_write2st64_b32 v200, v24, v25 offset0:216 offset1:224
	ds_write2st64_b32 v199, v9, v10 offset0:184 offset1:192
	ds_write2st64_b32 v200, v26, v27 offset0:232 offset1:240
	ds_write_b32 v200, v28 offset:63488
	ds_write2st64_b32 v199, v11, v12 offset0:200 offset1:208
	ds_write2st64_b32 v199, v29, v30 offset0:88 offset1:96
	ds_write2st64_b32 v199, v13, v14 offset0:216 offset1:224
	v_mul_f32_e32 v3, v31, v0
	v_mul_f32_e32 v5, v32, v0
	v_mul_f32_e32 v4, v15, v0
	ds_write2st64_b32 v199, v3, v5 offset0:104 offset1:112
	v_mul_f32_e32 v3, v16, v0
	v_mul_f32_e32 v2, v2, v0
	ds_write2st64_b32 v199, v4, v3 offset0:232 offset1:240
	v_mul_f32_e32 v3, v33, v0
	v_mul_f32_e32 v0, v17, v0
	ds_write_b32 v199, v0 offset:63488
	v_and_b32_e32 v0, 15, v84
	v_lshlrev_b32_e32 v8, 2, v0
	ds_write2st64_b32 v199, v3, v2 offset0:120 offset1:128
	v_ashrrev_i32_e32 v6, 4, v87
	s_movk_i32 s8, 0x204
	v_add_u32_e32 v2, -1, v8
	v_cmp_eq_u32_e32 vcc, 0, v0
	v_mul_lo_u32 v3, v6, s8
	v_add_u32_e32 v5, s17, v3
	v_cndmask_b32_e64 v7, v2, 0, vcc
	v_or_b32_e32 v2, 3, v8
	v_mov_b32_e32 v4, 0
	v_cmp_le_i32_e64 s[8:9], v7, v2
	v_mov_b32_e32 v9, 0
	s_waitcnt lgkmcnt(0)
	s_barrier
	s_and_saveexec_b64 s[10:11], s[8:9]
	s_cbranch_execz .LBB0_1426
	v_sub_u32_e32 v9, v8, v7
	v_add_u32_e32 v10, 4, v9
	v_cmp_lt_u32_e64 s[8:9], 1, v10
	s_mov_b64 s[14:15], -1
	v_mov_b32_e32 v9, 0
	s_and_saveexec_b64 s[12:13], s[8:9]
	s_cbranch_execz .LBB0_1421
	v_and_b32_e32 v11, -2, v10
	v_lshl_add_u32 v12, v7, 2, v5
	v_mov_b32_e32 v9, 0
	s_mov_b64 s[14:15], 0
	v_mov_b32_e32 v14, v11
	v_mov_b32_e32 v13, 0

.LBB0_1539:
	s_nop 1
	v_mov_b32_e32 v50, v9
	s_sub_i32 s8, 0x5e0, s7
	s_sub_i32 s16, 0x7ff, s7
	s_max_i32 s8, s8, -1
	s_ashr_i32 s9, s16, 6
	s_add_i32 s8, s8, 1
	s_add_i32 s10, s9, 1
	s_lshr_b32 s11, s8, 6
	s_lshl_b32 s8, -1, s10
	s_not_b32 s8, s8
	s_cmp_lg_u32 s9, 31
	v_mov_b32_e32 v51, v10
	s_cselect_b32 s10, s8, -1
	v_mov_b32_e32 v56, v12
	ds_read2st64_b32 v[34:35], v200 offset0:168 offset1:176
	ds_read2st64_b32 v[138:139], v199 offset0:120 offset1:128
	ds_read2st64_b32 v[36:37], v199 offset0:136 offset1:144
	ds_read2st64_b32 v[38:39], v200 offset0:184 offset1:192
	ds_read2st64_b32 v[40:41], v199 offset0:152 offset1:160
	ds_read2st64_b32 v[42:43], v200 offset0:200 offset1:208
	ds_read2st64_b32 v[44:45], v199 offset0:168 offset1:176
	ds_read2st64_b32 v[46:47], v200 offset0:216 offset1:224
	ds_read2st64_b32 v[48:49], v199 offset0:184 offset1:192
	ds_read2st64_b32 v[140:141], v200 offset0:232 offset1:240
	ds_read2st64_b32 v[54:55], v199 offset0:200 offset1:208
	v_mov_b32_e32 v57, v28
	ds_read2st64_b32 v[142:143], v199 offset0:88 offset1:96
	ds_read2st64_b32 v[144:145], v199 offset0:216 offset1:224
	ds_read2st64_b32 v[146:147], v199 offset0:104 offset1:112
	ds_read2st64_b32 v[148:149], v199 offset0:232 offset1:240
	ds_read_b32 v59, v200 offset:63488
	ds_read_b32 v219, v199 offset:63488
	s_lshl_b32 s11, -1, s11
	s_waitcnt lgkmcnt(7)
	v_mov_b32_e32 v61, v141
	s_waitcnt lgkmcnt(6)
	v_mov_b32_e32 v60, v54
	v_mov_b32_e32 v58, v55
	s_waitcnt vmcnt(0)
	v_lshlrev_b32_e32 v9, 16, v247
	v_mul_f32_e32 v9, 0xbfb8aa3b, v9
	v_exp_f32_e32 v9, v9
	s_nop 0
	v_add_f32_e32 v9, 1.0, v9
	v_div_scale_f32 v10, s[8:9], v9, v9, 1.0
	v_rcp_f32_e32 v12, v10
	v_div_scale_f32 v28, vcc, 1.0, v9, 1.0
	v_fma_f32 v53, -v10, v12, 1.0
	v_fmac_f32_e32 v12, v53, v12
	v_mul_f32_e32 v53, v28, v12
	v_fma_f32 v54, -v10, v53, v28
	v_fmac_f32_e32 v53, v54, v12
	v_fma_f32 v10, -v10, v53, v28
	v_div_fmas_f32 v10, v10, v12, v53
	v_div_fixup_f32 v9, v10, v9, 1.0
	v_div_scale_f32 v10, s[8:9], v52, v52, v9
	v_rcp_f32_e32 v12, v10
	v_div_scale_f32 v28, vcc, v9, v52, v9
	s_and_b32 s9, s11, s10
	v_fma_f32 v53, -v10, v12, 1.0
	v_fmac_f32_e32 v12, v53, v12
	v_mul_f32_e32 v53, v28, v12
	v_fma_f32 v54, -v10, v53, v28
	v_fmac_f32_e32 v53, v54, v12
	v_fma_f32 v10, -v10, v53, v28
	v_div_fmas_f32 v10, v10, v12, v53
	v_div_fixup_f32 v10, v10, v52, v9
	v_fmac_f32_e32 v140, v26, v10
	v_mov_b32_e32 v26, v11
	v_fma_f32 v9, v18, v10, v34
	v_fma_f32 v2, v2, v10, v139
	v_fmac_f32_e32 v35, v19, v10
	v_pk_fma_f32 v[150:151], v[50:51], v[10:11], v[48:49] op_sel_hi:[1,0,1]
	s_waitcnt lgkmcnt(1)
	v_pk_fma_f32 v[152:153], v[56:57], v[10:11], v[58:59] op_sel_hi:[1,0,1]
	v_fma_f32 v139, v29, v10, v142
	v_fma_f32 v141, v13, v10, v144
	v_fmac_f32_e32 v143, v30, v10
	v_fmac_f32_e32 v145, v14, v10
	v_fma_f32 v142, v31, v10, v146
	v_fma_f32 v144, v15, v10, v148
	v_fmac_f32_e32 v147, v32, v10
	v_fmac_f32_e32 v149, v16, v10
	v_fmac_f32_e32 v138, v33, v10
	s_waitcnt lgkmcnt(0)
	v_fmac_f32_e32 v219, v17, v10
	v_pk_fma_f32 v[154:155], v[26:27], v[10:11], v[60:61] op_sel_hi:[1,0,1]
	s_cmp_lg_u32 s9, 0
	v_fma_f32 v3, v3, v10, v36
	v_fma_f32 v12, v20, v10, v38
	v_fmac_f32_e32 v37, v4, v10
	v_fmac_f32_e32 v39, v21, v10
	v_fma_f32 v4, v5, v10, v40
	v_fma_f32 v5, v22, v10, v42
	v_fmac_f32_e32 v41, v6, v10
	v_fmac_f32_e32 v43, v23, v10
	v_fma_f32 v6, v7, v10, v44
	v_fma_f32 v7, v24, v10, v46
	v_fmac_f32_e32 v45, v8, v10
	v_fmac_f32_e32 v47, v25, v10
	ds_write2st64_b32 v200, v9, v35 offset0:168 offset1:176
	ds_write2st64_b32 v199, v3, v37 offset0:136 offset1:144
	ds_write2st64_b32 v200, v12, v39 offset0:184 offset1:192
	ds_write2st64_b32 v199, v4, v41 offset0:152 offset1:160
	ds_write2st64_b32 v200, v5, v43 offset0:200 offset1:208
	ds_write2st64_b32 v199, v6, v45 offset0:168 offset1:176
	ds_write2st64_b32 v200, v7, v47 offset0:216 offset1:224
	ds_write2st64_b32 v199, v150, v151 offset0:184 offset1:192
	ds_write_b32 v200, v153 offset:63488
	ds_write2st64_b32 v199, v139, v143 offset0:88 offset1:96
	ds_write2st64_b32 v199, v141, v145 offset0:216 offset1:224
	ds_write2st64_b32 v199, v142, v147 offset0:104 offset1:112
	ds_write2st64_b32 v199, v144, v149 offset0:232 offset1:240
	ds_write2st64_b32 v199, v138, v2 offset0:120 offset1:128
	ds_write2st64_b32 v200, v140, v155 offset0:232 offset1:240
	ds_write2st64_b32 v199, v154, v152 offset0:200 offset1:208
	ds_write_b32 v199, v219 offset:63488
	s_cbranch_scc0 .LBB0_1618
	s_add_u32 s8, s20, s46
	s_addc_u32 s13, s21, 0
	s_add_u32 s10, s8, 0x1700
	s_addc_u32 s11, s13, 0
	s_add_u32 s12, s8, 0x1600
	s_addc_u32 s13, s13, 0
	s_ff1_i32_b32 s8, s9
	s_add_i32 s14, s9, -1
	s_and_b32 s9, s14, s9
	s_mul_i32 s17, s8, 0x68000
	s_add_u32 s14, s12, s17
	s_addc_u32 s15, s13, 0
	global_load_dwordx4 v[2:5], v0, s[14:15]
	s_add_u32 s14, s10, s17
	s_addc_u32 s15, s11, 0
	global_load_dwordx4 v[6:9], v0, s[14:15]
	v_mov_b32_e32 v10, v1
	v_mov_b32_e32 v11, v1
	v_mov_b32_e32 v12, v1
	v_mov_b32_e32 v13, v1
	v_mov_b32_e32 v14, v1
	v_mov_b32_e32 v15, v1
	v_mov_b32_e32 v16, v1
	v_mov_b32_e32 v17, v1
	v_mov_b32_e32 v18, v1
	v_mov_b32_e32 v19, v1
	v_mov_b32_e32 v20, v1
	v_mov_b32_e32 v21, v1
	v_mov_b32_e32 v22, v1
	v_mov_b32_e32 v23, v1
	v_mov_b32_e32 v24, v1
	v_mov_b32_e32 v25, v1
	v_mov_b32_e32 v26, v1
	v_mov_b32_e32 v27, v1
	v_mov_b32_e32 v28, v1
	v_mov_b32_e32 v29, v1
	v_mov_b32_e32 v30, v1
	v_mov_b32_e32 v31, v1
	v_lshl_add_u64 v[156:157], s[10:11], 0, v[0:1]
	v_mov_b32_e32 v146, 0
	s_mov_b32 s17, 0
	s_addk_i32 s7, 0xf85e
	v_mov_b32_e32 v148, 0xf149f2ca
	v_mov_b32_e32 v158, 0
	v_mov_b32_e32 v159, v146
	v_mov_b32_e32 v160, 0
	v_mov_b32_e32 v161, v146
	v_mov_b32_e32 v162, 0
	v_mov_b32_e32 v163, v146
	v_mov_b32_e32 v164, 0
	v_mov_b32_e32 v165, v146
	v_mov_b32_e32 v166, 0
	v_mov_b32_e32 v167, v146
	v_mov_b32_e32 v168, 0
	v_mov_b32_e32 v169, v146
	v_mov_b32_e32 v170, 0
	v_mov_b32_e32 v171, v146
	v_mov_b32_e32 v172, 0
	v_mov_b32_e32 v173, v146
	v_mov_b32_e32 v174, 0
	v_mov_b32_e32 v175, v146
	v_mov_b32_e32 v176, 0
	v_mov_b32_e32 v177, v146
	v_mov_b32_e32 v178, 0
	v_mov_b32_e32 v179, v146
	v_mov_b32_e32 v180, 0
	v_mov_b32_e32 v181, v146
	v_mov_b32_e32 v182, 0
	v_mov_b32_e32 v183, v146
	v_mov_b32_e32 v184, 0
	v_mov_b32_e32 v185, v146
	v_mov_b32_e32 v186, 0
	v_mov_b32_e32 v187, v146
	v_mov_b32_e32 v188, 0
	v_mov_b32_e32 v189, v146
	s_mov_b32 s18, s8
	s_waitcnt vmcnt(1)
	ds_write_b128 v135, v[2:5]
	s_waitcnt vmcnt(0)
	ds_write_b128 v134, v[6:9] offset:9216
	v_mov_b32_e32 v2, v1
	v_mov_b32_e32 v3, v1
	v_mov_b32_e32 v4, v1
	v_mov_b32_e32 v5, v1
	v_mov_b32_e32 v6, v1
	v_mov_b32_e32 v7, v1
	v_mov_b32_e32 v8, v1
	v_mov_b32_e32 v9, v1
	v_lshl_add_u64 v[134:135], s[12:13], 0, v[0:1]
	v_mov_b32_e32 v0, v1
	v_mov_b64_e32 v[32:33], v[30:31]
	v_mov_b64_e32 v[30:31], v[28:29]
	v_mov_b64_e32 v[28:29], v[26:27]
	v_mov_b64_e32 v[26:27], v[24:25]
	v_mov_b64_e32 v[24:25], v[22:23]
	v_mov_b64_e32 v[22:23], v[20:21]
	v_mov_b64_e32 v[20:21], v[18:19]
	v_mov_b64_e32 v[18:19], v[16:17]
	v_mov_b64_e32 v[16:17], v[14:15]
	v_mov_b64_e32 v[14:15], v[12:13]
	v_mov_b64_e32 v[12:13], v[10:11]
	v_mov_b64_e32 v[10:11], v[8:9]
	v_mov_b64_e32 v[8:9], v[6:7]
	v_mov_b64_e32 v[6:7], v[4:5]
	v_mov_b64_e32 v[4:5], v[2:3]
	v_mov_b64_e32 v[2:3], v[0:1]
	s_waitcnt lgkmcnt(0)
	s_barrier
